# v46 + O3 light jobs dealt 4/9/10 to blocks with 4/3/3 GEMM tiles (even per-block work)
# speedup vs baseline: 1.0011x; 1.0011x over previous
.LBB0_446:
	s_cmpk_lg_u32 s38, 0x100
	s_cbranch_scc1 .Lo3_orig
	s_cmpk_ge_i32 s8, 0x340
	s_cbranch_scc1 .Lo3_light
	s_add_i32 s8, s8, 0x100
	s_cmpk_lt_i32 s8, 0x340
	s_cbranch_scc1 .LBB0_447
	s_movk_i32 s0, 0x340
	s_movk_i32 s1, 0x400
	s_cmpk_ge_u32 s92, 0x40
	s_cselect_b32 s0, s1, s0
	s_movk_i32 s1, 0x800
	s_cmpk_ge_u32 s92, 0xc0
	s_cselect_b32 s0, s1, s0
	s_add_i32 s8, s0, s92
	s_branch .LBB0_447
.Lo3_light:
	s_movk_i32 s0, 0x40
	s_movk_i32 s1, 0x80
	s_cmpk_ge_u32 s92, 0x40
	s_cselect_b32 s0, s1, s0
	s_movk_i32 s1, 0x40
	s_cmpk_ge_u32 s92, 0xc0
	s_cselect_b32 s0, s1, s0
	s_add_i32 s8, s8, s0
	s_movk_i32 s0, 0x440
	s_movk_i32 s1, 0x8c0
	s_cmpk_ge_u32 s92, 0x40
	s_cselect_b32 s0, s1, s0
	s_movk_i32 s1, 0xb40
	s_cmpk_ge_u32 s92, 0xc0
	s_cselect_b32 s0, s1, s0
	s_cmp_ge_i32 s8, s0
	s_cbranch_scc1 .LBB0_519
	s_branch .LBB0_447
